# column-sliced gather: sub-phase A pieces processed in interleaved pairs with one transposing DPP reduction per 8 pieces; C accumulators initialised by the first multiply; c in a scratch buffer
# speedup vs baseline: 1.7584x; 1.0051x over previous
.Lgy_A_1:
	v_lshrrev_b32_e32 v142, 6, v162
	v_readlane_b32 s2, v242, 0
	v_readlane_b32 s59, v241, 24
	v_readfirstlane_b32 s29, v142
	s_and_b32 s28, s2, 7
	s_lshr_b32 s2, s2, 3
	s_lshl_b32 s2, s2, 2
	s_add_u32 s54, s2, s29
	s_lshr_b32 s59, s59, 3
	s_load_dwordx2 s[88:89], s[0:1], 0x1a8
	s_load_dwordx2 s[92:93], s[0:1], 0x130
	v_readlane_b32 s40, v240, 8
	v_readlane_b32 s41, v240, 9
	v_and_b32_e32 v142, 7, v168
	v_lshlrev_b32_e32 v160, 2, v168
	s_lshl_b32 s32, s28, 7
	v_lshl_add_u32 v138, v142, 4, s32
	v_and_b32_e32 v143, 0xf8, v168
	v_add_u32_e32 v130, 0, v143
	v_add_u32_e32 v131, 1, v143
	v_add_u32_e32 v132, 2, v143
	v_add_u32_e32 v133, 3, v143
	v_add_u32_e32 v134, 4, v143
	v_add_u32_e32 v135, 5, v143
	v_add_u32_e32 v136, 6, v143
	v_add_u32_e32 v137, 7, v143
	v_lshlrev_b32_e32 v130, 2, v130
	v_lshlrev_b32_e32 v131, 2, v131
	v_lshlrev_b32_e32 v132, 2, v132
	v_lshlrev_b32_e32 v133, 2, v133
	v_lshlrev_b32_e32 v134, 2, v134
	v_lshlrev_b32_e32 v135, 2, v135
	v_lshlrev_b32_e32 v136, 2, v136
	v_lshlrev_b32_e32 v137, 2, v137
	s_lshl_b32 s32, s28, 8
	v_lshl_add_u32 v161, v142, 5, s32
	s_mov_b32 s4, 0xcccccccc
	s_mov_b32 s5, 0xcccccccc
	s_mov_b32 s6, 0xaaaaaaaa
	s_mov_b32 s7, 0xaaaaaaaa
	s_waitcnt lgkmcnt(0)
	s_mul_i32 s32, s28, 0x840000
	s_add_u32 s92, s92, s32
	s_addc_u32 s93, s93, 0
	s_nop 4
	s_cmp_lt_u32 s54, 0x4200
	s_cbranch_scc0 .Lgy_Adone_6
	s_min_u32 s98, s54, 0x41ff
	s_lshl_b32 s98, s98, 9
	s_add_u32 s52, s88, s98
	s_addc_u32 s53, s89, 0
	global_load_dword v144, v160, s[52:53]
	global_load_dword v145, v160, s[52:53] offset:256
	s_add_u32 s99, s54, s59
	s_min_u32 s98, s99, 0x41ff
	s_lshl_b32 s98, s98, 9
	s_add_u32 s52, s88, s98
	s_addc_u32 s53, s89, 0
	global_load_dword v150, v160, s[52:53]
	global_load_dword v151, v160, s[52:53] offset:256
	s_min_u32 s98, s54, 0x41ff
	s_lshl_b32 s98, s98, 11
	s_add_u32 s52, s74, s98
	s_addc_u32 s53, s75, 0
	global_load_dwordx4 v[152:155], v161, s[52:53]
	global_load_dwordx4 v[156:159], v161, s[52:53] offset:16
	s_waitcnt vmcnt(0)
	ds_bpermute_b32 v16, v130, v144
	ds_bpermute_b32 v17, v134, v144
	ds_bpermute_b32 v18, v132, v144
	ds_bpermute_b32 v19, v136, v144
	ds_bpermute_b32 v20, v131, v144
	ds_bpermute_b32 v21, v135, v144
	ds_bpermute_b32 v22, v133, v144
	ds_bpermute_b32 v23, v137, v144
	ds_bpermute_b32 v24, v130, v145
	ds_bpermute_b32 v25, v134, v145
	ds_bpermute_b32 v26, v132, v145
	ds_bpermute_b32 v27, v136, v145
	ds_bpermute_b32 v28, v131, v145
	ds_bpermute_b32 v29, v135, v145
	ds_bpermute_b32 v30, v133, v145
	ds_bpermute_b32 v31, v137, v145
	s_waitcnt lgkmcnt(0)
	v_lshl_add_u32 v16, v16, 10, v138
	v_lshl_add_u32 v17, v17, 10, v138
	v_lshl_add_u32 v18, v18, 10, v138
	v_lshl_add_u32 v19, v19, 10, v138
	v_lshl_add_u32 v20, v20, 10, v138
	v_lshl_add_u32 v21, v21, 10, v138
	v_lshl_add_u32 v22, v22, 10, v138
	v_lshl_add_u32 v23, v23, 10, v138
	v_lshl_add_u32 v24, v24, 10, v138
	v_lshl_add_u32 v25, v25, 10, v138
	v_lshl_add_u32 v26, v26, 10, v138
	v_lshl_add_u32 v27, v27, 10, v138
	v_lshl_add_u32 v28, v28, 10, v138
	v_lshl_add_u32 v29, v29, 10, v138
	v_lshl_add_u32 v30, v30, 10, v138
	v_lshl_add_u32 v31, v31, 10, v138
	global_load_dwordx4 v[48:51], v16, s[40:41]
	global_load_dwordx4 v[52:55], v17, s[40:41]
	global_load_dwordx4 v[56:59], v18, s[40:41]
	global_load_dwordx4 v[60:63], v19, s[40:41]
	global_load_dwordx4 v[64:67], v20, s[40:41]
	global_load_dwordx4 v[68:71], v21, s[40:41]
	global_load_dwordx4 v[72:75], v22, s[40:41]
	global_load_dwordx4 v[76:79], v23, s[40:41]
	global_load_dwordx4 v[80:83], v24, s[40:41]
	global_load_dwordx4 v[84:87], v25, s[40:41]
	global_load_dwordx4 v[88:91], v26, s[40:41]
	global_load_dwordx4 v[92:95], v27, s[40:41]
	global_load_dwordx4 v[96:99], v28, s[40:41]
	global_load_dwordx4 v[100:103], v29, s[40:41]
	global_load_dwordx4 v[104:107], v30, s[40:41]
	global_load_dwordx4 v[108:111], v31, s[40:41]
	ds_bpermute_b32 v16, v130, v150
	ds_bpermute_b32 v17, v134, v150
	ds_bpermute_b32 v18, v132, v150
	ds_bpermute_b32 v19, v136, v150
	ds_bpermute_b32 v20, v131, v150
	ds_bpermute_b32 v21, v135, v150
	ds_bpermute_b32 v22, v133, v150
	ds_bpermute_b32 v23, v137, v150
	ds_bpermute_b32 v24, v130, v151
	ds_bpermute_b32 v25, v134, v151
	ds_bpermute_b32 v26, v132, v151
	ds_bpermute_b32 v27, v136, v151
	ds_bpermute_b32 v28, v131, v151
	ds_bpermute_b32 v29, v135, v151
	ds_bpermute_b32 v30, v133, v151
	ds_bpermute_b32 v31, v137, v151
	s_waitcnt lgkmcnt(0)
	v_lshl_add_u32 v16, v16, 10, v138
	v_lshl_add_u32 v17, v17, 10, v138
	v_lshl_add_u32 v18, v18, 10, v138
	v_lshl_add_u32 v19, v19, 10, v138
	v_lshl_add_u32 v20, v20, 10, v138
	v_lshl_add_u32 v21, v21, 10, v138
	v_lshl_add_u32 v22, v22, 10, v138
	v_lshl_add_u32 v23, v23, 10, v138
	v_lshl_add_u32 v24, v24, 10, v138
	v_lshl_add_u32 v25, v25, 10, v138
	v_lshl_add_u32 v26, v26, 10, v138
	v_lshl_add_u32 v27, v27, 10, v138
	v_lshl_add_u32 v28, v28, 10, v138
	v_lshl_add_u32 v29, v29, 10, v138
	v_lshl_add_u32 v30, v30, 10, v138
	v_lshl_add_u32 v31, v31, 10, v138
	v_lshlrev_b32_e32 v0, 16, v152
	v_and_b32_e32 v1, 0xffff0000, v152
	v_lshlrev_b32_e32 v2, 16, v153
	v_and_b32_e32 v3, 0xffff0000, v153
	v_lshlrev_b32_e32 v4, 16, v154
	v_and_b32_e32 v5, 0xffff0000, v154
	v_lshlrev_b32_e32 v6, 16, v155
	v_and_b32_e32 v7, 0xffff0000, v155
	v_lshlrev_b32_e32 v8, 16, v156
	v_and_b32_e32 v9, 0xffff0000, v156
	v_lshlrev_b32_e32 v10, 16, v157
	v_and_b32_e32 v11, 0xffff0000, v157
	v_lshlrev_b32_e32 v12, 16, v158
	v_and_b32_e32 v13, 0xffff0000, v158
	v_lshlrev_b32_e32 v14, 16, v159
	v_and_b32_e32 v15, 0xffff0000, v159
.Lgy_Atok_7:
	s_add_u32 s99, s54, s59
	s_add_u32 s96, s99, s59
	s_min_u32 s98, s96, 0x41ff
	s_lshl_b32 s98, s98, 9
	s_add_u32 s52, s88, s98
	s_addc_u32 s53, s89, 0
	global_load_dword v150, v160, s[52:53]
	global_load_dword v151, v160, s[52:53] offset:256
	s_min_u32 s98, s99, 0x41ff
	s_lshl_b32 s98, s98, 11
	s_add_u32 s52, s74, s98
	s_addc_u32 s53, s75, 0
	global_load_dwordx4 v[152:155], v161, s[52:53]
	global_load_dwordx4 v[156:159], v161, s[52:53] offset:16
	s_waitcnt vmcnt(18)
	v_cvt_pk_f32_fp8_e32 v[112:113], v48
	v_cvt_pk_f32_fp8_sdwa v[114:115], v48 src0_sel:WORD_1
	v_cvt_pk_f32_fp8_e32 v[116:117], v49
	v_cvt_pk_f32_fp8_sdwa v[118:119], v49 src0_sel:WORD_1
	v_cvt_pk_f32_fp8_e32 v[120:121], v50
	v_cvt_pk_f32_fp8_sdwa v[122:123], v50 src0_sel:WORD_1
	v_cvt_pk_f32_fp8_e32 v[124:125], v51
	v_cvt_pk_f32_fp8_sdwa v[126:127], v51 src0_sel:WORD_1
	global_load_dwordx4 v[48:51], v16, s[40:41]
	v_cvt_pk_f32_fp8_e32 v[32:33], v52
	v_cvt_pk_f32_fp8_sdwa v[34:35], v52 src0_sel:WORD_1
	v_cvt_pk_f32_fp8_e32 v[36:37], v53
	v_cvt_pk_f32_fp8_sdwa v[38:39], v53 src0_sel:WORD_1
	v_cvt_pk_f32_fp8_e32 v[40:41], v54
	v_cvt_pk_f32_fp8_sdwa v[42:43], v54 src0_sel:WORD_1
	v_cvt_pk_f32_fp8_e32 v[44:45], v55
	v_cvt_pk_f32_fp8_sdwa v[46:47], v55 src0_sel:WORD_1
	global_load_dwordx4 v[52:55], v17, s[40:41]
	v_pk_mul_f32 v[142:143], v[112:113], v[0:1]
	v_pk_mul_f32 v[144:145], v[32:33], v[0:1]
	v_pk_fma_f32 v[142:143], v[114:115], v[2:3], v[142:143]
	v_pk_fma_f32 v[144:145], v[34:35], v[2:3], v[144:145]
	v_pk_fma_f32 v[142:143], v[116:117], v[4:5], v[142:143]
	v_pk_fma_f32 v[144:145], v[36:37], v[4:5], v[144:145]
	v_pk_fma_f32 v[142:143], v[118:119], v[6:7], v[142:143]
	v_pk_fma_f32 v[144:145], v[38:39], v[6:7], v[144:145]
	v_pk_fma_f32 v[142:143], v[120:121], v[8:9], v[142:143]
	v_pk_fma_f32 v[144:145], v[40:41], v[8:9], v[144:145]
	v_pk_fma_f32 v[142:143], v[122:123], v[10:11], v[142:143]
	v_pk_fma_f32 v[144:145], v[42:43], v[10:11], v[144:145]
	v_pk_fma_f32 v[142:143], v[124:125], v[12:13], v[142:143]
	v_pk_fma_f32 v[144:145], v[44:45], v[12:13], v[144:145]
	v_pk_fma_f32 v[142:143], v[126:127], v[14:15], v[142:143]
	v_pk_fma_f32 v[144:145], v[46:47], v[14:15], v[144:145]
	v_add_f32_e32 v146, v142, v143
	v_add_f32_e32 v147, v144, v145
	s_waitcnt vmcnt(18)
	v_cvt_pk_f32_fp8_e32 v[112:113], v56
	v_cvt_pk_f32_fp8_sdwa v[114:115], v56 src0_sel:WORD_1
	v_cvt_pk_f32_fp8_e32 v[116:117], v57
	v_cvt_pk_f32_fp8_sdwa v[118:119], v57 src0_sel:WORD_1
	v_cvt_pk_f32_fp8_e32 v[120:121], v58
	v_cvt_pk_f32_fp8_sdwa v[122:123], v58 src0_sel:WORD_1
	v_cvt_pk_f32_fp8_e32 v[124:125], v59
	v_cvt_pk_f32_fp8_sdwa v[126:127], v59 src0_sel:WORD_1
	global_load_dwordx4 v[56:59], v18, s[40:41]
	v_cvt_pk_f32_fp8_e32 v[32:33], v60
	v_cvt_pk_f32_fp8_sdwa v[34:35], v60 src0_sel:WORD_1
	v_cvt_pk_f32_fp8_e32 v[36:37], v61
	v_cvt_pk_f32_fp8_sdwa v[38:39], v61 src0_sel:WORD_1
	v_cvt_pk_f32_fp8_e32 v[40:41], v62
	v_cvt_pk_f32_fp8_sdwa v[42:43], v62 src0_sel:WORD_1
	v_cvt_pk_f32_fp8_e32 v[44:45], v63
	v_cvt_pk_f32_fp8_sdwa v[46:47], v63 src0_sel:WORD_1
	global_load_dwordx4 v[60:63], v19, s[40:41]
	v_pk_mul_f32 v[142:143], v[112:113], v[0:1]
	v_pk_mul_f32 v[144:145], v[32:33], v[0:1]
	v_pk_fma_f32 v[142:143], v[114:115], v[2:3], v[142:143]
	v_pk_fma_f32 v[144:145], v[34:35], v[2:3], v[144:145]
	v_pk_fma_f32 v[142:143], v[116:117], v[4:5], v[142:143]
	v_pk_fma_f32 v[144:145], v[36:37], v[4:5], v[144:145]
	v_pk_fma_f32 v[142:143], v[118:119], v[6:7], v[142:143]
	v_pk_fma_f32 v[144:145], v[38:39], v[6:7], v[144:145]
	v_pk_fma_f32 v[142:143], v[120:121], v[8:9], v[142:143]
	v_pk_fma_f32 v[144:145], v[40:41], v[8:9], v[144:145]
	v_pk_fma_f32 v[142:143], v[122:123], v[10:11], v[142:143]
	v_pk_fma_f32 v[144:145], v[42:43], v[10:11], v[144:145]
	v_pk_fma_f32 v[142:143], v[124:125], v[12:13], v[142:143]
	v_pk_fma_f32 v[144:145], v[44:45], v[12:13], v[144:145]
	v_pk_fma_f32 v[142:143], v[126:127], v[14:15], v[142:143]
	v_pk_fma_f32 v[144:145], v[46:47], v[14:15], v[144:145]
	v_add_f32_e32 v148, v142, v143
	v_add_f32_e32 v149, v144, v145
	s_waitcnt vmcnt(18)
	v_cvt_pk_f32_fp8_e32 v[112:113], v64
	v_cvt_pk_f32_fp8_sdwa v[114:115], v64 src0_sel:WORD_1
	v_cvt_pk_f32_fp8_e32 v[116:117], v65
	v_cvt_pk_f32_fp8_sdwa v[118:119], v65 src0_sel:WORD_1
	v_cvt_pk_f32_fp8_e32 v[120:121], v66
	v_cvt_pk_f32_fp8_sdwa v[122:123], v66 src0_sel:WORD_1
	v_cvt_pk_f32_fp8_e32 v[124:125], v67
	v_cvt_pk_f32_fp8_sdwa v[126:127], v67 src0_sel:WORD_1
	global_load_dwordx4 v[64:67], v20, s[40:41]
	v_cvt_pk_f32_fp8_e32 v[32:33], v68
	v_cvt_pk_f32_fp8_sdwa v[34:35], v68 src0_sel:WORD_1
	v_cvt_pk_f32_fp8_e32 v[36:37], v69
	v_cvt_pk_f32_fp8_sdwa v[38:39], v69 src0_sel:WORD_1
	v_cvt_pk_f32_fp8_e32 v[40:41], v70
	v_cvt_pk_f32_fp8_sdwa v[42:43], v70 src0_sel:WORD_1
	v_cvt_pk_f32_fp8_e32 v[44:45], v71
	v_cvt_pk_f32_fp8_sdwa v[46:47], v71 src0_sel:WORD_1
	global_load_dwordx4 v[68:71], v21, s[40:41]
	v_pk_mul_f32 v[142:143], v[112:113], v[0:1]
	v_pk_mul_f32 v[144:145], v[32:33], v[0:1]
	v_pk_fma_f32 v[142:143], v[114:115], v[2:3], v[142:143]
	v_pk_fma_f32 v[144:145], v[34:35], v[2:3], v[144:145]
	v_pk_fma_f32 v[142:143], v[116:117], v[4:5], v[142:143]
	v_pk_fma_f32 v[144:145], v[36:37], v[4:5], v[144:145]
	v_pk_fma_f32 v[142:143], v[118:119], v[6:7], v[142:143]
	v_pk_fma_f32 v[144:145], v[38:39], v[6:7], v[144:145]
	v_pk_fma_f32 v[142:143], v[120:121], v[8:9], v[142:143]
	v_pk_fma_f32 v[144:145], v[40:41], v[8:9], v[144:145]
	v_pk_fma_f32 v[142:143], v[122:123], v[10:11], v[142:143]
	v_pk_fma_f32 v[144:145], v[42:43], v[10:11], v[144:145]
	v_pk_fma_f32 v[142:143], v[124:125], v[12:13], v[142:143]
	v_pk_fma_f32 v[144:145], v[44:45], v[12:13], v[144:145]
	v_pk_fma_f32 v[142:143], v[126:127], v[14:15], v[142:143]
	v_pk_fma_f32 v[144:145], v[46:47], v[14:15], v[144:145]
	v_add_f32_e32 v190, v142, v143
	v_add_f32_e32 v191, v144, v145
	s_waitcnt vmcnt(18)
	v_cvt_pk_f32_fp8_e32 v[112:113], v72
	v_cvt_pk_f32_fp8_sdwa v[114:115], v72 src0_sel:WORD_1
	v_cvt_pk_f32_fp8_e32 v[116:117], v73
	v_cvt_pk_f32_fp8_sdwa v[118:119], v73 src0_sel:WORD_1
	v_cvt_pk_f32_fp8_e32 v[120:121], v74
	v_cvt_pk_f32_fp8_sdwa v[122:123], v74 src0_sel:WORD_1
	v_cvt_pk_f32_fp8_e32 v[124:125], v75
	v_cvt_pk_f32_fp8_sdwa v[126:127], v75 src0_sel:WORD_1
	global_load_dwordx4 v[72:75], v22, s[40:41]
	v_cvt_pk_f32_fp8_e32 v[32:33], v76
	v_cvt_pk_f32_fp8_sdwa v[34:35], v76 src0_sel:WORD_1
	v_cvt_pk_f32_fp8_e32 v[36:37], v77
	v_cvt_pk_f32_fp8_sdwa v[38:39], v77 src0_sel:WORD_1
	v_cvt_pk_f32_fp8_e32 v[40:41], v78
	v_cvt_pk_f32_fp8_sdwa v[42:43], v78 src0_sel:WORD_1
	v_cvt_pk_f32_fp8_e32 v[44:45], v79
	v_cvt_pk_f32_fp8_sdwa v[46:47], v79 src0_sel:WORD_1
	global_load_dwordx4 v[76:79], v23, s[40:41]
	v_pk_mul_f32 v[142:143], v[112:113], v[0:1]
	v_pk_mul_f32 v[144:145], v[32:33], v[0:1]
	v_pk_fma_f32 v[142:143], v[114:115], v[2:3], v[142:143]
	v_pk_fma_f32 v[144:145], v[34:35], v[2:3], v[144:145]
	v_pk_fma_f32 v[142:143], v[116:117], v[4:5], v[142:143]
	v_pk_fma_f32 v[144:145], v[36:37], v[4:5], v[144:145]
	v_pk_fma_f32 v[142:143], v[118:119], v[6:7], v[142:143]
	v_pk_fma_f32 v[144:145], v[38:39], v[6:7], v[144:145]
	v_pk_fma_f32 v[142:143], v[120:121], v[8:9], v[142:143]
	v_pk_fma_f32 v[144:145], v[40:41], v[8:9], v[144:145]
	v_pk_fma_f32 v[142:143], v[122:123], v[10:11], v[142:143]
	v_pk_fma_f32 v[144:145], v[42:43], v[10:11], v[144:145]
	v_pk_fma_f32 v[142:143], v[124:125], v[12:13], v[142:143]
	v_pk_fma_f32 v[144:145], v[44:45], v[12:13], v[144:145]
	v_pk_fma_f32 v[142:143], v[126:127], v[14:15], v[142:143]
	v_pk_fma_f32 v[144:145], v[46:47], v[14:15], v[144:145]
	v_add_f32_e32 v141, v142, v143
	v_add_f32_e32 v128, v144, v145
	s_nop 0
	v_add_f32_dpp v142, v146, v146 row_half_mirror row_mask:0xf bank_mask:0x5
	v_add_f32_dpp v142, v147, v147 row_half_mirror row_mask:0xf bank_mask:0xa
	v_add_f32_dpp v143, v148, v148 row_half_mirror row_mask:0xf bank_mask:0x5
	v_add_f32_dpp v143, v149, v149 row_half_mirror row_mask:0xf bank_mask:0xa
	v_add_f32_dpp v144, v190, v190 row_half_mirror row_mask:0xf bank_mask:0x5
	v_add_f32_dpp v144, v191, v191 row_half_mirror row_mask:0xf bank_mask:0xa
	v_add_f32_dpp v145, v141, v141 row_half_mirror row_mask:0xf bank_mask:0x5
	v_add_f32_dpp v145, v128, v128 row_half_mirror row_mask:0xf bank_mask:0xa
	s_nop 0
	v_add_f32_dpp v146, v142, v142 quad_perm:[3,2,1,0] row_mask:0xf bank_mask:0xf
	v_add_f32_dpp v147, v143, v143 quad_perm:[3,2,1,0] row_mask:0xf bank_mask:0xf
	v_cndmask_b32_e64 v148, v146, v147, s[4:5]
	v_add_f32_dpp v146, v144, v144 quad_perm:[3,2,1,0] row_mask:0xf bank_mask:0xf
	v_add_f32_dpp v147, v145, v145 quad_perm:[3,2,1,0] row_mask:0xf bank_mask:0xf
	v_cndmask_b32_e64 v149, v146, v147, s[4:5]
	s_nop 1
	v_add_f32_dpp v146, v148, v148 quad_perm:[1,0,3,2] row_mask:0xf bank_mask:0xf
	v_add_f32_dpp v147, v149, v149 quad_perm:[1,0,3,2] row_mask:0xf bank_mask:0xf
	v_cndmask_b32_e64 v139, v146, v147, s[6:7]
	s_waitcnt vmcnt(18)
	v_cvt_pk_f32_fp8_e32 v[112:113], v80
	v_cvt_pk_f32_fp8_sdwa v[114:115], v80 src0_sel:WORD_1
	v_cvt_pk_f32_fp8_e32 v[116:117], v81
	v_cvt_pk_f32_fp8_sdwa v[118:119], v81 src0_sel:WORD_1
	v_cvt_pk_f32_fp8_e32 v[120:121], v82
	v_cvt_pk_f32_fp8_sdwa v[122:123], v82 src0_sel:WORD_1
	v_cvt_pk_f32_fp8_e32 v[124:125], v83
	v_cvt_pk_f32_fp8_sdwa v[126:127], v83 src0_sel:WORD_1
	global_load_dwordx4 v[80:83], v24, s[40:41]
	v_cvt_pk_f32_fp8_e32 v[32:33], v84
	v_cvt_pk_f32_fp8_sdwa v[34:35], v84 src0_sel:WORD_1
	v_cvt_pk_f32_fp8_e32 v[36:37], v85
	v_cvt_pk_f32_fp8_sdwa v[38:39], v85 src0_sel:WORD_1
	v_cvt_pk_f32_fp8_e32 v[40:41], v86
	v_cvt_pk_f32_fp8_sdwa v[42:43], v86 src0_sel:WORD_1
	v_cvt_pk_f32_fp8_e32 v[44:45], v87
	v_cvt_pk_f32_fp8_sdwa v[46:47], v87 src0_sel:WORD_1
	global_load_dwordx4 v[84:87], v25, s[40:41]
	v_pk_mul_f32 v[142:143], v[112:113], v[0:1]
	v_pk_mul_f32 v[144:145], v[32:33], v[0:1]
	v_pk_fma_f32 v[142:143], v[114:115], v[2:3], v[142:143]
	v_pk_fma_f32 v[144:145], v[34:35], v[2:3], v[144:145]
	v_pk_fma_f32 v[142:143], v[116:117], v[4:5], v[142:143]
	v_pk_fma_f32 v[144:145], v[36:37], v[4:5], v[144:145]
	v_pk_fma_f32 v[142:143], v[118:119], v[6:7], v[142:143]
	v_pk_fma_f32 v[144:145], v[38:39], v[6:7], v[144:145]
	v_pk_fma_f32 v[142:143], v[120:121], v[8:9], v[142:143]
	v_pk_fma_f32 v[144:145], v[40:41], v[8:9], v[144:145]
	v_pk_fma_f32 v[142:143], v[122:123], v[10:11], v[142:143]
	v_pk_fma_f32 v[144:145], v[42:43], v[10:11], v[144:145]
	v_pk_fma_f32 v[142:143], v[124:125], v[12:13], v[142:143]
	v_pk_fma_f32 v[144:145], v[44:45], v[12:13], v[144:145]
	v_pk_fma_f32 v[142:143], v[126:127], v[14:15], v[142:143]
	v_pk_fma_f32 v[144:145], v[46:47], v[14:15], v[144:145]
	v_add_f32_e32 v146, v142, v143
	v_add_f32_e32 v147, v144, v145
	s_waitcnt vmcnt(18)
	v_cvt_pk_f32_fp8_e32 v[112:113], v88
	v_cvt_pk_f32_fp8_sdwa v[114:115], v88 src0_sel:WORD_1
	v_cvt_pk_f32_fp8_e32 v[116:117], v89
	v_cvt_pk_f32_fp8_sdwa v[118:119], v89 src0_sel:WORD_1
	v_cvt_pk_f32_fp8_e32 v[120:121], v90
	v_cvt_pk_f32_fp8_sdwa v[122:123], v90 src0_sel:WORD_1
	v_cvt_pk_f32_fp8_e32 v[124:125], v91
	v_cvt_pk_f32_fp8_sdwa v[126:127], v91 src0_sel:WORD_1
	global_load_dwordx4 v[88:91], v26, s[40:41]
	v_cvt_pk_f32_fp8_e32 v[32:33], v92
	v_cvt_pk_f32_fp8_sdwa v[34:35], v92 src0_sel:WORD_1
	v_cvt_pk_f32_fp8_e32 v[36:37], v93
	v_cvt_pk_f32_fp8_sdwa v[38:39], v93 src0_sel:WORD_1
	v_cvt_pk_f32_fp8_e32 v[40:41], v94
	v_cvt_pk_f32_fp8_sdwa v[42:43], v94 src0_sel:WORD_1
	v_cvt_pk_f32_fp8_e32 v[44:45], v95
	v_cvt_pk_f32_fp8_sdwa v[46:47], v95 src0_sel:WORD_1
	global_load_dwordx4 v[92:95], v27, s[40:41]
	v_pk_mul_f32 v[142:143], v[112:113], v[0:1]
	v_pk_mul_f32 v[144:145], v[32:33], v[0:1]
	v_pk_fma_f32 v[142:143], v[114:115], v[2:3], v[142:143]
	v_pk_fma_f32 v[144:145], v[34:35], v[2:3], v[144:145]
	v_pk_fma_f32 v[142:143], v[116:117], v[4:5], v[142:143]
	v_pk_fma_f32 v[144:145], v[36:37], v[4:5], v[144:145]
	v_pk_fma_f32 v[142:143], v[118:119], v[6:7], v[142:143]
	v_pk_fma_f32 v[144:145], v[38:39], v[6:7], v[144:145]
	v_pk_fma_f32 v[142:143], v[120:121], v[8:9], v[142:143]
	v_pk_fma_f32 v[144:145], v[40:41], v[8:9], v[144:145]
	v_pk_fma_f32 v[142:143], v[122:123], v[10:11], v[142:143]
	v_pk_fma_f32 v[144:145], v[42:43], v[10:11], v[144:145]
	v_pk_fma_f32 v[142:143], v[124:125], v[12:13], v[142:143]
	v_pk_fma_f32 v[144:145], v[44:45], v[12:13], v[144:145]
	v_pk_fma_f32 v[142:143], v[126:127], v[14:15], v[142:143]
	v_pk_fma_f32 v[144:145], v[46:47], v[14:15], v[144:145]
	v_add_f32_e32 v148, v142, v143
	v_add_f32_e32 v149, v144, v145
	s_waitcnt vmcnt(18)
	v_cvt_pk_f32_fp8_e32 v[112:113], v96
	v_cvt_pk_f32_fp8_sdwa v[114:115], v96 src0_sel:WORD_1
	v_cvt_pk_f32_fp8_e32 v[116:117], v97
	v_cvt_pk_f32_fp8_sdwa v[118:119], v97 src0_sel:WORD_1
	v_cvt_pk_f32_fp8_e32 v[120:121], v98
	v_cvt_pk_f32_fp8_sdwa v[122:123], v98 src0_sel:WORD_1
	v_cvt_pk_f32_fp8_e32 v[124:125], v99
	v_cvt_pk_f32_fp8_sdwa v[126:127], v99 src0_sel:WORD_1
	global_load_dwordx4 v[96:99], v28, s[40:41]
	v_cvt_pk_f32_fp8_e32 v[32:33], v100
	v_cvt_pk_f32_fp8_sdwa v[34:35], v100 src0_sel:WORD_1
	v_cvt_pk_f32_fp8_e32 v[36:37], v101
	v_cvt_pk_f32_fp8_sdwa v[38:39], v101 src0_sel:WORD_1
	v_cvt_pk_f32_fp8_e32 v[40:41], v102
	v_cvt_pk_f32_fp8_sdwa v[42:43], v102 src0_sel:WORD_1
	v_cvt_pk_f32_fp8_e32 v[44:45], v103
	v_cvt_pk_f32_fp8_sdwa v[46:47], v103 src0_sel:WORD_1
	global_load_dwordx4 v[100:103], v29, s[40:41]
	v_pk_mul_f32 v[142:143], v[112:113], v[0:1]
	v_pk_mul_f32 v[144:145], v[32:33], v[0:1]
	v_pk_fma_f32 v[142:143], v[114:115], v[2:3], v[142:143]
	v_pk_fma_f32 v[144:145], v[34:35], v[2:3], v[144:145]
	v_pk_fma_f32 v[142:143], v[116:117], v[4:5], v[142:143]
	v_pk_fma_f32 v[144:145], v[36:37], v[4:5], v[144:145]
	v_pk_fma_f32 v[142:143], v[118:119], v[6:7], v[142:143]
	v_pk_fma_f32 v[144:145], v[38:39], v[6:7], v[144:145]
	v_pk_fma_f32 v[142:143], v[120:121], v[8:9], v[142:143]
	v_pk_fma_f32 v[144:145], v[40:41], v[8:9], v[144:145]
	v_pk_fma_f32 v[142:143], v[122:123], v[10:11], v[142:143]
	v_pk_fma_f32 v[144:145], v[42:43], v[10:11], v[144:145]
	v_pk_fma_f32 v[142:143], v[124:125], v[12:13], v[142:143]
	v_pk_fma_f32 v[144:145], v[44:45], v[12:13], v[144:145]
	v_pk_fma_f32 v[142:143], v[126:127], v[14:15], v[142:143]
	v_pk_fma_f32 v[144:145], v[46:47], v[14:15], v[144:145]
	v_add_f32_e32 v190, v142, v143
	v_add_f32_e32 v191, v144, v145
	s_waitcnt vmcnt(18)
	v_cvt_pk_f32_fp8_e32 v[112:113], v104
	v_cvt_pk_f32_fp8_sdwa v[114:115], v104 src0_sel:WORD_1
	v_cvt_pk_f32_fp8_e32 v[116:117], v105
	v_cvt_pk_f32_fp8_sdwa v[118:119], v105 src0_sel:WORD_1
	v_cvt_pk_f32_fp8_e32 v[120:121], v106
	v_cvt_pk_f32_fp8_sdwa v[122:123], v106 src0_sel:WORD_1
	v_cvt_pk_f32_fp8_e32 v[124:125], v107
	v_cvt_pk_f32_fp8_sdwa v[126:127], v107 src0_sel:WORD_1
	global_load_dwordx4 v[104:107], v30, s[40:41]
	v_cvt_pk_f32_fp8_e32 v[32:33], v108
	v_cvt_pk_f32_fp8_sdwa v[34:35], v108 src0_sel:WORD_1
	v_cvt_pk_f32_fp8_e32 v[36:37], v109
	v_cvt_pk_f32_fp8_sdwa v[38:39], v109 src0_sel:WORD_1
	v_cvt_pk_f32_fp8_e32 v[40:41], v110
	v_cvt_pk_f32_fp8_sdwa v[42:43], v110 src0_sel:WORD_1
	v_cvt_pk_f32_fp8_e32 v[44:45], v111
	v_cvt_pk_f32_fp8_sdwa v[46:47], v111 src0_sel:WORD_1
	global_load_dwordx4 v[108:111], v31, s[40:41]
	v_pk_mul_f32 v[142:143], v[112:113], v[0:1]
	v_pk_mul_f32 v[144:145], v[32:33], v[0:1]
	v_pk_fma_f32 v[142:143], v[114:115], v[2:3], v[142:143]
	v_pk_fma_f32 v[144:145], v[34:35], v[2:3], v[144:145]
	v_pk_fma_f32 v[142:143], v[116:117], v[4:5], v[142:143]
	v_pk_fma_f32 v[144:145], v[36:37], v[4:5], v[144:145]
	v_pk_fma_f32 v[142:143], v[118:119], v[6:7], v[142:143]
	v_pk_fma_f32 v[144:145], v[38:39], v[6:7], v[144:145]
	v_pk_fma_f32 v[142:143], v[120:121], v[8:9], v[142:143]
	v_pk_fma_f32 v[144:145], v[40:41], v[8:9], v[144:145]
	v_pk_fma_f32 v[142:143], v[122:123], v[10:11], v[142:143]
	v_pk_fma_f32 v[144:145], v[42:43], v[10:11], v[144:145]
	v_pk_fma_f32 v[142:143], v[124:125], v[12:13], v[142:143]
	v_pk_fma_f32 v[144:145], v[44:45], v[12:13], v[144:145]
	v_pk_fma_f32 v[142:143], v[126:127], v[14:15], v[142:143]
	v_pk_fma_f32 v[144:145], v[46:47], v[14:15], v[144:145]
	v_add_f32_e32 v141, v142, v143
	v_add_f32_e32 v128, v144, v145
	s_nop 0
	v_add_f32_dpp v142, v146, v146 row_half_mirror row_mask:0xf bank_mask:0x5
	v_add_f32_dpp v142, v147, v147 row_half_mirror row_mask:0xf bank_mask:0xa
	v_add_f32_dpp v143, v148, v148 row_half_mirror row_mask:0xf bank_mask:0x5
	v_add_f32_dpp v143, v149, v149 row_half_mirror row_mask:0xf bank_mask:0xa
	v_add_f32_dpp v144, v190, v190 row_half_mirror row_mask:0xf bank_mask:0x5
	v_add_f32_dpp v144, v191, v191 row_half_mirror row_mask:0xf bank_mask:0xa
	v_add_f32_dpp v145, v141, v141 row_half_mirror row_mask:0xf bank_mask:0x5
	v_add_f32_dpp v145, v128, v128 row_half_mirror row_mask:0xf bank_mask:0xa
	s_nop 0
	v_add_f32_dpp v146, v142, v142 quad_perm:[3,2,1,0] row_mask:0xf bank_mask:0xf
	v_add_f32_dpp v147, v143, v143 quad_perm:[3,2,1,0] row_mask:0xf bank_mask:0xf
	v_cndmask_b32_e64 v148, v146, v147, s[4:5]
	v_add_f32_dpp v146, v144, v144 quad_perm:[3,2,1,0] row_mask:0xf bank_mask:0xf
	v_add_f32_dpp v147, v145, v145 quad_perm:[3,2,1,0] row_mask:0xf bank_mask:0xf
	v_cndmask_b32_e64 v149, v146, v147, s[4:5]
	s_nop 1
	v_add_f32_dpp v146, v148, v148 quad_perm:[1,0,3,2] row_mask:0xf bank_mask:0xf
	v_add_f32_dpp v147, v149, v149 quad_perm:[1,0,3,2] row_mask:0xf bank_mask:0xf
	v_cndmask_b32_e64 v140, v146, v147, s[6:7]
	s_lshl_b32 s98, s54, 9
	s_add_u32 s52, s92, s98
	s_addc_u32 s53, s93, 0
	global_store_dword v160, v139, s[52:53]
	global_store_dword v160, v140, s[52:53] offset:256
	s_waitcnt vmcnt(16)
	ds_bpermute_b32 v16, v130, v150
	ds_bpermute_b32 v17, v134, v150
	ds_bpermute_b32 v18, v132, v150
	ds_bpermute_b32 v19, v136, v150
	ds_bpermute_b32 v20, v131, v150
	ds_bpermute_b32 v21, v135, v150
	ds_bpermute_b32 v22, v133, v150
	ds_bpermute_b32 v23, v137, v150
	ds_bpermute_b32 v24, v130, v151
	ds_bpermute_b32 v25, v134, v151
	ds_bpermute_b32 v26, v132, v151
	ds_bpermute_b32 v27, v136, v151
	ds_bpermute_b32 v28, v131, v151
	ds_bpermute_b32 v29, v135, v151
	ds_bpermute_b32 v30, v133, v151
	ds_bpermute_b32 v31, v137, v151
	v_lshlrev_b32_e32 v0, 16, v152
	v_and_b32_e32 v1, 0xffff0000, v152
	v_lshlrev_b32_e32 v2, 16, v153
	v_and_b32_e32 v3, 0xffff0000, v153
	v_lshlrev_b32_e32 v4, 16, v154
	v_and_b32_e32 v5, 0xffff0000, v154
	v_lshlrev_b32_e32 v6, 16, v155
	v_and_b32_e32 v7, 0xffff0000, v155
	v_lshlrev_b32_e32 v8, 16, v156
	v_and_b32_e32 v9, 0xffff0000, v156
	v_lshlrev_b32_e32 v10, 16, v157
	v_and_b32_e32 v11, 0xffff0000, v157
	v_lshlrev_b32_e32 v12, 16, v158
	v_and_b32_e32 v13, 0xffff0000, v158
	v_lshlrev_b32_e32 v14, 16, v159
	v_and_b32_e32 v15, 0xffff0000, v159
	s_waitcnt lgkmcnt(0)
	v_lshl_add_u32 v16, v16, 10, v138
	v_lshl_add_u32 v17, v17, 10, v138
	v_lshl_add_u32 v18, v18, 10, v138
	v_lshl_add_u32 v19, v19, 10, v138
	v_lshl_add_u32 v20, v20, 10, v138
	v_lshl_add_u32 v21, v21, 10, v138
	v_lshl_add_u32 v22, v22, 10, v138
	v_lshl_add_u32 v23, v23, 10, v138
	v_lshl_add_u32 v24, v24, 10, v138
	v_lshl_add_u32 v25, v25, 10, v138
	v_lshl_add_u32 v26, v26, 10, v138
	v_lshl_add_u32 v27, v27, 10, v138
	v_lshl_add_u32 v28, v28, 10, v138
	v_lshl_add_u32 v29, v29, 10, v138
	v_lshl_add_u32 v30, v30, 10, v138
	v_lshl_add_u32 v31, v31, 10, v138
	s_mov_b32 s54, s99
	s_cmp_lt_u32 s54, 0x4200
	s_cbranch_scc1 .Lgy_Atok_7

.Lgy_Btok_8:
	s_lshl_b32 s98, s54, 9
	s_add_u32 s52, s88, s98
	s_addc_u32 s53, s89, 0
	global_load_dword v0, v160, s[52:53]
	global_load_dword v1, v160, s[52:53] offset:256
	s_add_u32 s46, s90, s98
	s_addc_u32 s47, s91, 0
	global_load_dword v2, v160, s[46:47]
	global_load_dword v3, v160, s[46:47] offset:256
	s_add_u32 s52, s92, s98
	s_addc_u32 s53, s93, 0
	global_load_dword v8, v160, s[52:53]
	global_load_dword v9, v160, s[52:53] offset:256
	s_add_u32 s52, s52, 0x840000
	s_addc_u32 s53, s53, 0
	global_load_dword v10, v160, s[52:53]
	global_load_dword v11, v160, s[52:53] offset:256
	s_add_u32 s52, s52, 0x840000
	s_addc_u32 s53, s53, 0
	global_load_dword v12, v160, s[52:53]
	global_load_dword v13, v160, s[52:53] offset:256
	s_add_u32 s52, s52, 0x840000
	s_addc_u32 s53, s53, 0
	global_load_dword v14, v160, s[52:53]
	global_load_dword v15, v160, s[52:53] offset:256
	s_add_u32 s52, s52, 0x840000
	s_addc_u32 s53, s53, 0
	global_load_dword v16, v160, s[52:53]
	global_load_dword v17, v160, s[52:53] offset:256
	s_add_u32 s52, s52, 0x840000
	s_addc_u32 s53, s53, 0
	global_load_dword v18, v160, s[52:53]
	global_load_dword v19, v160, s[52:53] offset:256
	s_add_u32 s52, s52, 0x840000
	s_addc_u32 s53, s53, 0
	global_load_dword v20, v160, s[52:53]
	global_load_dword v21, v160, s[52:53] offset:256
	s_add_u32 s52, s52, 0x840000
	s_addc_u32 s53, s53, 0
	global_load_dword v22, v160, s[52:53]
	global_load_dword v23, v160, s[52:53] offset:256
	s_waitcnt vmcnt(18)
	v_lshlrev_b32_e32 v142, 2, v0
	v_lshlrev_b32_e32 v143, 2, v1
	global_load_dword v4, v142, s[44:45]
	global_load_dword v6, v142, s[50:51]
	global_load_dword v5, v143, s[44:45]
	global_load_dword v7, v143, s[50:51]
	s_waitcnt vmcnt(4)
	v_add_f32_e32 v8, v8, v10
	v_add_f32_e32 v8, v8, v12
	v_add_f32_e32 v8, v8, v14
	v_add_f32_e32 v8, v8, v16
	v_add_f32_e32 v8, v8, v18
	v_add_f32_e32 v8, v8, v20
	v_add_f32_e32 v8, v8, v22
	v_add_f32_e32 v9, v9, v11
	v_add_f32_e32 v9, v9, v13
	v_add_f32_e32 v9, v9, v15
	v_add_f32_e32 v9, v9, v17
	v_add_f32_e32 v9, v9, v19
	v_add_f32_e32 v9, v9, v21
	v_add_f32_e32 v9, v9, v23
	s_waitcnt vmcnt(0)
	v_mul_f32_e32 v144, v4, v8
	v_mul_f32_e32 v145, 0x3d372713, v144
	v_mul_f32_e32 v145, v144, v145
	v_fma_f32 v145, v144, v145, v144
	v_mul_f32_e32 v145, 0x3f4c422a, v145
	v_mul_f32_e32 v145, -2.0, v145
	v_mul_f32_e32 v145, 0x3fb8aa3b, v145
	v_exp_f32_e32 v145, v145
	v_mul_f32_e32 v2, v2, v6
	v_add_f32_e32 v145, 1.0, v145
	v_rcp_f32_e32 v145, v145
	s_nop 0
	v_mul_f32_e32 v144, v144, v145
	v_mul_f32_e32 v2, v2, v144
	v_mul_f32_e32 v146, v5, v9
	v_mul_f32_e32 v147, 0x3d372713, v146
	v_mul_f32_e32 v147, v146, v147
	v_fma_f32 v147, v146, v147, v146
	v_mul_f32_e32 v147, 0x3f4c422a, v147
	v_mul_f32_e32 v147, -2.0, v147
	v_mul_f32_e32 v147, 0x3fb8aa3b, v147
	v_exp_f32_e32 v147, v147
	v_mul_f32_e32 v3, v3, v7
	v_add_f32_e32 v147, 1.0, v147
	v_rcp_f32_e32 v147, v147
	s_nop 0
	v_mul_f32_e32 v146, v146, v147
	v_mul_f32_e32 v3, v3, v146
	s_add_u32 s46, s92, s98
	s_addc_u32 s47, s93, 0
	s_add_u32 s46, s46, 0x5000000
	s_addc_u32 s47, s47, 0
	global_store_dword v160, v2, s[46:47]
	global_store_dword v160, v3, s[46:47] offset:256
	s_add_u32 s54, s54, s59
	s_cmp_lt_u32 s54, 0x4200
	s_cbranch_scc1 .Lgy_Btok_8

.Lgy_C_3:
	v_lshrrev_b32_e32 v142, 6, v162
	v_readlane_b32 s2, v242, 0
	v_readlane_b32 s59, v241, 24
	v_readfirstlane_b32 s29, v142
	s_and_b32 s28, s2, 7
	s_lshr_b32 s2, s2, 3
	s_lshl_b32 s2, s2, 2
	s_add_u32 s54, s2, s29
	s_lshr_b32 s59, s59, 3
	s_load_dwordx2 s[88:89], s[0:1], 0x1a8
	s_load_dwordx2 s[90:91], s[0:1], 0x130
	s_load_dwordx2 s[92:93], s[0:1], 0x120
	s_load_dwordx2 s[94:95], s[0:1], 0xc8
	v_readlane_b32 s40, v240, 10
	v_readlane_b32 s41, v240, 11
	v_and_b32_e32 v142, 7, v168
	v_lshlrev_b32_e32 v160, 2, v168
	s_lshl_b32 s32, s28, 7
	v_lshl_add_u32 v138, v142, 4, s32
	v_and_b32_e32 v143, 0xf8, v168
	v_add_u32_e32 v130, 0, v143
	v_add_u32_e32 v131, 1, v143
	v_add_u32_e32 v132, 2, v143
	v_add_u32_e32 v133, 3, v143
	v_add_u32_e32 v134, 4, v143
	v_add_u32_e32 v135, 5, v143
	v_add_u32_e32 v136, 6, v143
	v_add_u32_e32 v137, 7, v143
	v_lshlrev_b32_e32 v130, 2, v130
	v_lshlrev_b32_e32 v131, 2, v131
	v_lshlrev_b32_e32 v132, 2, v132
	v_lshlrev_b32_e32 v133, 2, v133
	v_lshlrev_b32_e32 v134, 2, v134
	v_lshlrev_b32_e32 v135, 2, v135
	v_lshlrev_b32_e32 v136, 2, v136
	v_lshlrev_b32_e32 v137, 2, v137
	v_lshrrev_b32_e32 v144, 3, v168
	v_lshlrev_b32_e32 v144, 3, v144
	s_lshl_b32 s32, s28, 9
	v_lshl_add_u32 v188, v142, 6, s32
	v_add_u32_e32 v188, v188, v144
	s_mov_b32 s16, 0x3fd744fd
	s_waitcnt lgkmcnt(0)
	s_add_u32 s90, s90, 0x5000000
	s_addc_u32 s91, s91, 0
	s_nop 4
	s_cmp_lt_u32 s54, 0x4200
	s_cbranch_scc0 .Lgy_Cdone_10
	s_min_u32 s98, s54, 0x41ff
	s_lshl_b32 s98, s98, 9
	s_add_u32 s52, s88, s98
	s_addc_u32 s53, s89, 0
	global_load_dword v144, v160, s[52:53]
	global_load_dword v145, v160, s[52:53] offset:256
	s_add_u32 s99, s54, s59
	s_min_u32 s98, s99, 0x41ff
	s_lshl_b32 s98, s98, 9
	s_add_u32 s52, s88, s98
	s_addc_u32 s53, s89, 0
	global_load_dword v150, v160, s[52:53]
	global_load_dword v151, v160, s[52:53] offset:256
	s_min_u32 s98, s54, 0x41ff
	s_lshl_b32 s98, s98, 9
	s_add_u32 s52, s90, s98
	s_addc_u32 s53, s91, 0
	global_load_dword v194, v160, s[52:53]
	global_load_dword v195, v160, s[52:53] offset:256
	s_waitcnt vmcnt(0)
	ds_bpermute_b32 v16, v130, v144
	ds_bpermute_b32 v17, v131, v144
	ds_bpermute_b32 v18, v132, v144
	ds_bpermute_b32 v19, v133, v144
	ds_bpermute_b32 v20, v134, v144
	ds_bpermute_b32 v21, v135, v144
	ds_bpermute_b32 v22, v136, v144
	ds_bpermute_b32 v23, v137, v144
	ds_bpermute_b32 v24, v130, v145
	ds_bpermute_b32 v25, v131, v145
	ds_bpermute_b32 v26, v132, v145
	ds_bpermute_b32 v27, v133, v145
	ds_bpermute_b32 v28, v134, v145
	ds_bpermute_b32 v29, v135, v145
	ds_bpermute_b32 v30, v136, v145
	ds_bpermute_b32 v31, v137, v145
	s_waitcnt lgkmcnt(0)
	v_lshl_add_u32 v16, v16, 10, v138
	v_lshl_add_u32 v17, v17, 10, v138
	v_lshl_add_u32 v18, v18, 10, v138
	v_lshl_add_u32 v19, v19, 10, v138
	v_lshl_add_u32 v20, v20, 10, v138
	v_lshl_add_u32 v21, v21, 10, v138
	v_lshl_add_u32 v22, v22, 10, v138
	v_lshl_add_u32 v23, v23, 10, v138
	v_lshl_add_u32 v24, v24, 10, v138
	v_lshl_add_u32 v25, v25, 10, v138
	v_lshl_add_u32 v26, v26, 10, v138
	v_lshl_add_u32 v27, v27, 10, v138
	v_lshl_add_u32 v28, v28, 10, v138
	v_lshl_add_u32 v29, v29, 10, v138
	v_lshl_add_u32 v30, v30, 10, v138
	v_lshl_add_u32 v31, v31, 10, v138
	global_load_dwordx4 v[48:51], v16, s[40:41]
	global_load_dwordx4 v[52:55], v17, s[40:41]
	global_load_dwordx4 v[56:59], v18, s[40:41]
	global_load_dwordx4 v[60:63], v19, s[40:41]
	global_load_dwordx4 v[64:67], v20, s[40:41]
	global_load_dwordx4 v[68:71], v21, s[40:41]
	global_load_dwordx4 v[72:75], v22, s[40:41]
	global_load_dwordx4 v[76:79], v23, s[40:41]
	global_load_dwordx4 v[80:83], v24, s[40:41]
	global_load_dwordx4 v[84:87], v25, s[40:41]
	global_load_dwordx4 v[88:91], v26, s[40:41]
	global_load_dwordx4 v[92:95], v27, s[40:41]
	global_load_dwordx4 v[96:99], v28, s[40:41]
	global_load_dwordx4 v[100:103], v29, s[40:41]
	global_load_dwordx4 v[104:107], v30, s[40:41]
	global_load_dwordx4 v[108:111], v31, s[40:41]
	ds_bpermute_b32 v16, v130, v150
	ds_bpermute_b32 v17, v131, v150
	ds_bpermute_b32 v18, v132, v150
	ds_bpermute_b32 v19, v133, v150
	ds_bpermute_b32 v20, v134, v150
	ds_bpermute_b32 v21, v135, v150
	ds_bpermute_b32 v22, v136, v150
	ds_bpermute_b32 v23, v137, v150
	ds_bpermute_b32 v24, v130, v151
	ds_bpermute_b32 v25, v131, v151
	ds_bpermute_b32 v26, v132, v151
	ds_bpermute_b32 v27, v133, v151
	ds_bpermute_b32 v28, v134, v151
	ds_bpermute_b32 v29, v135, v151
	ds_bpermute_b32 v30, v136, v151
	ds_bpermute_b32 v31, v137, v151
	s_waitcnt lgkmcnt(0)
	v_lshl_add_u32 v16, v16, 10, v138
	v_lshl_add_u32 v17, v17, 10, v138
	v_lshl_add_u32 v18, v18, 10, v138
	v_lshl_add_u32 v19, v19, 10, v138
	v_lshl_add_u32 v20, v20, 10, v138
	v_lshl_add_u32 v21, v21, 10, v138
	v_lshl_add_u32 v22, v22, 10, v138
	v_lshl_add_u32 v23, v23, 10, v138
	v_lshl_add_u32 v24, v24, 10, v138
	v_lshl_add_u32 v25, v25, 10, v138
	v_lshl_add_u32 v26, v26, 10, v138
	v_lshl_add_u32 v27, v27, 10, v138
	v_lshl_add_u32 v28, v28, 10, v138
	v_lshl_add_u32 v29, v29, 10, v138
	v_lshl_add_u32 v30, v30, 10, v138
	v_lshl_add_u32 v31, v31, 10, v138
	ds_bpermute_b32 v32, v130, v194
	ds_bpermute_b32 v33, v131, v194
	ds_bpermute_b32 v34, v132, v194
	ds_bpermute_b32 v35, v133, v194
	ds_bpermute_b32 v36, v134, v194
	ds_bpermute_b32 v37, v135, v194
	ds_bpermute_b32 v38, v136, v194
	ds_bpermute_b32 v39, v137, v194
	ds_bpermute_b32 v40, v130, v195
	ds_bpermute_b32 v41, v131, v195
	ds_bpermute_b32 v42, v132, v195
	ds_bpermute_b32 v43, v133, v195
	ds_bpermute_b32 v44, v134, v195
	ds_bpermute_b32 v45, v135, v195
	ds_bpermute_b32 v46, v136, v195
	ds_bpermute_b32 v47, v137, v195
.Lgy_Ctok_11:
	s_add_u32 s99, s54, s59
	s_add_u32 s96, s99, s59
	s_min_u32 s98, s96, 0x41ff
	s_lshl_b32 s98, s98, 9
	s_add_u32 s52, s88, s98
	s_addc_u32 s53, s89, 0
	global_load_dword v150, v160, s[52:53]
	global_load_dword v151, v160, s[52:53] offset:256
	s_min_u32 s98, s99, 0x41ff
	s_lshl_b32 s98, s98, 9
	s_add_u32 s52, s90, s98
	s_addc_u32 s53, s91, 0
	global_load_dword v194, v160, s[52:53]
	global_load_dword v195, v160, s[52:53] offset:256
	s_lshl_b32 s98, s54, 12
	s_add_u32 s52, s70, s98
	s_addc_u32 s53, s71, 0
	global_load_dwordx2 v[190:191], v188, s[52:53]
	s_cmp_lt_u32 s54, 0x2000
	s_cselect_b32 s98, 0, 1
	s_cmp_lt_u32 s54, 0x4000
	s_cselect_b32 s98, s98, 2
	s_add_u32 s98, s98, s27
	s_mul_i32 s98, s98, 0x6000
	s_add_u32 s98, s98, 0x5000
	s_add_u32 s52, s94, s98
	s_addc_u32 s53, s95, 0
	global_load_dwordx2 v[192:193], v188, s[52:53]
	s_waitcnt lgkmcnt(0)
	s_waitcnt vmcnt(21)
	v_cvt_pk_f32_fp8_e32 v[112:113], v48
	v_cvt_pk_f32_fp8_sdwa v[114:115], v48 src0_sel:WORD_1
	v_cvt_pk_f32_fp8_e32 v[116:117], v49
	v_cvt_pk_f32_fp8_sdwa v[118:119], v49 src0_sel:WORD_1
	v_cvt_pk_f32_fp8_e32 v[120:121], v50
	v_cvt_pk_f32_fp8_sdwa v[122:123], v50 src0_sel:WORD_1
	v_cvt_pk_f32_fp8_e32 v[124:125], v51
	v_cvt_pk_f32_fp8_sdwa v[126:127], v51 src0_sel:WORD_1
	global_load_dwordx4 v[48:51], v16, s[40:41]
	v_pk_mul_f32 v[0:1], v[112:113], v[32:33] op_sel_hi:[1,0]
	v_pk_mul_f32 v[2:3], v[114:115], v[32:33] op_sel_hi:[1,0]
	v_pk_mul_f32 v[4:5], v[116:117], v[32:33] op_sel_hi:[1,0]
	v_pk_mul_f32 v[6:7], v[118:119], v[32:33] op_sel_hi:[1,0]
	v_pk_mul_f32 v[8:9], v[120:121], v[32:33] op_sel_hi:[1,0]
	v_pk_mul_f32 v[10:11], v[122:123], v[32:33] op_sel_hi:[1,0]
	v_pk_mul_f32 v[12:13], v[124:125], v[32:33] op_sel_hi:[1,0]
	v_pk_mul_f32 v[14:15], v[126:127], v[32:33] op_sel_hi:[1,0]
	s_waitcnt vmcnt(21)
	v_cvt_pk_f32_fp8_e32 v[112:113], v52
	v_cvt_pk_f32_fp8_sdwa v[114:115], v52 src0_sel:WORD_1
	v_cvt_pk_f32_fp8_e32 v[116:117], v53
	v_cvt_pk_f32_fp8_sdwa v[118:119], v53 src0_sel:WORD_1
	v_cvt_pk_f32_fp8_e32 v[120:121], v54
	v_cvt_pk_f32_fp8_sdwa v[122:123], v54 src0_sel:WORD_1
	v_cvt_pk_f32_fp8_e32 v[124:125], v55
	v_cvt_pk_f32_fp8_sdwa v[126:127], v55 src0_sel:WORD_1
	global_load_dwordx4 v[52:55], v17, s[40:41]
	v_pk_fma_f32 v[0:1], v[112:113], v[32:33], v[0:1] op_sel:[0,1,0] op_sel_hi:[1,1,1]
	v_pk_fma_f32 v[2:3], v[114:115], v[32:33], v[2:3] op_sel:[0,1,0] op_sel_hi:[1,1,1]
	v_pk_fma_f32 v[4:5], v[116:117], v[32:33], v[4:5] op_sel:[0,1,0] op_sel_hi:[1,1,1]
	v_pk_fma_f32 v[6:7], v[118:119], v[32:33], v[6:7] op_sel:[0,1,0] op_sel_hi:[1,1,1]
	v_pk_fma_f32 v[8:9], v[120:121], v[32:33], v[8:9] op_sel:[0,1,0] op_sel_hi:[1,1,1]
	v_pk_fma_f32 v[10:11], v[122:123], v[32:33], v[10:11] op_sel:[0,1,0] op_sel_hi:[1,1,1]
	v_pk_fma_f32 v[12:13], v[124:125], v[32:33], v[12:13] op_sel:[0,1,0] op_sel_hi:[1,1,1]
	v_pk_fma_f32 v[14:15], v[126:127], v[32:33], v[14:15] op_sel:[0,1,0] op_sel_hi:[1,1,1]
	s_waitcnt vmcnt(21)
	v_cvt_pk_f32_fp8_e32 v[112:113], v56
	v_cvt_pk_f32_fp8_sdwa v[114:115], v56 src0_sel:WORD_1
	v_cvt_pk_f32_fp8_e32 v[116:117], v57
	v_cvt_pk_f32_fp8_sdwa v[118:119], v57 src0_sel:WORD_1
	v_cvt_pk_f32_fp8_e32 v[120:121], v58
	v_cvt_pk_f32_fp8_sdwa v[122:123], v58 src0_sel:WORD_1
	v_cvt_pk_f32_fp8_e32 v[124:125], v59
	v_cvt_pk_f32_fp8_sdwa v[126:127], v59 src0_sel:WORD_1
	global_load_dwordx4 v[56:59], v18, s[40:41]
	v_pk_fma_f32 v[0:1], v[112:113], v[34:35], v[0:1] op_sel_hi:[1,0,1]
	v_pk_fma_f32 v[2:3], v[114:115], v[34:35], v[2:3] op_sel_hi:[1,0,1]
	v_pk_fma_f32 v[4:5], v[116:117], v[34:35], v[4:5] op_sel_hi:[1,0,1]
	v_pk_fma_f32 v[6:7], v[118:119], v[34:35], v[6:7] op_sel_hi:[1,0,1]
	v_pk_fma_f32 v[8:9], v[120:121], v[34:35], v[8:9] op_sel_hi:[1,0,1]
	v_pk_fma_f32 v[10:11], v[122:123], v[34:35], v[10:11] op_sel_hi:[1,0,1]
	v_pk_fma_f32 v[12:13], v[124:125], v[34:35], v[12:13] op_sel_hi:[1,0,1]
	v_pk_fma_f32 v[14:15], v[126:127], v[34:35], v[14:15] op_sel_hi:[1,0,1]
	s_waitcnt vmcnt(21)
	v_cvt_pk_f32_fp8_e32 v[112:113], v60
	v_cvt_pk_f32_fp8_sdwa v[114:115], v60 src0_sel:WORD_1
	v_cvt_pk_f32_fp8_e32 v[116:117], v61
	v_cvt_pk_f32_fp8_sdwa v[118:119], v61 src0_sel:WORD_1
	v_cvt_pk_f32_fp8_e32 v[120:121], v62
	v_cvt_pk_f32_fp8_sdwa v[122:123], v62 src0_sel:WORD_1
	v_cvt_pk_f32_fp8_e32 v[124:125], v63
	v_cvt_pk_f32_fp8_sdwa v[126:127], v63 src0_sel:WORD_1
	global_load_dwordx4 v[60:63], v19, s[40:41]
	v_pk_fma_f32 v[0:1], v[112:113], v[34:35], v[0:1] op_sel:[0,1,0] op_sel_hi:[1,1,1]
	v_pk_fma_f32 v[2:3], v[114:115], v[34:35], v[2:3] op_sel:[0,1,0] op_sel_hi:[1,1,1]
	v_pk_fma_f32 v[4:5], v[116:117], v[34:35], v[4:5] op_sel:[0,1,0] op_sel_hi:[1,1,1]
	v_pk_fma_f32 v[6:7], v[118:119], v[34:35], v[6:7] op_sel:[0,1,0] op_sel_hi:[1,1,1]
	v_pk_fma_f32 v[8:9], v[120:121], v[34:35], v[8:9] op_sel:[0,1,0] op_sel_hi:[1,1,1]
	v_pk_fma_f32 v[10:11], v[122:123], v[34:35], v[10:11] op_sel:[0,1,0] op_sel_hi:[1,1,1]
	v_pk_fma_f32 v[12:13], v[124:125], v[34:35], v[12:13] op_sel:[0,1,0] op_sel_hi:[1,1,1]
	v_pk_fma_f32 v[14:15], v[126:127], v[34:35], v[14:15] op_sel:[0,1,0] op_sel_hi:[1,1,1]
	s_waitcnt vmcnt(21)
	v_cvt_pk_f32_fp8_e32 v[112:113], v64
	v_cvt_pk_f32_fp8_sdwa v[114:115], v64 src0_sel:WORD_1
	v_cvt_pk_f32_fp8_e32 v[116:117], v65
	v_cvt_pk_f32_fp8_sdwa v[118:119], v65 src0_sel:WORD_1
	v_cvt_pk_f32_fp8_e32 v[120:121], v66
	v_cvt_pk_f32_fp8_sdwa v[122:123], v66 src0_sel:WORD_1
	v_cvt_pk_f32_fp8_e32 v[124:125], v67
	v_cvt_pk_f32_fp8_sdwa v[126:127], v67 src0_sel:WORD_1
	global_load_dwordx4 v[64:67], v20, s[40:41]
	v_pk_fma_f32 v[0:1], v[112:113], v[36:37], v[0:1] op_sel_hi:[1,0,1]
	v_pk_fma_f32 v[2:3], v[114:115], v[36:37], v[2:3] op_sel_hi:[1,0,1]
	v_pk_fma_f32 v[4:5], v[116:117], v[36:37], v[4:5] op_sel_hi:[1,0,1]
	v_pk_fma_f32 v[6:7], v[118:119], v[36:37], v[6:7] op_sel_hi:[1,0,1]
	v_pk_fma_f32 v[8:9], v[120:121], v[36:37], v[8:9] op_sel_hi:[1,0,1]
	v_pk_fma_f32 v[10:11], v[122:123], v[36:37], v[10:11] op_sel_hi:[1,0,1]
	v_pk_fma_f32 v[12:13], v[124:125], v[36:37], v[12:13] op_sel_hi:[1,0,1]
	v_pk_fma_f32 v[14:15], v[126:127], v[36:37], v[14:15] op_sel_hi:[1,0,1]
	s_waitcnt vmcnt(21)
	v_cvt_pk_f32_fp8_e32 v[112:113], v68
	v_cvt_pk_f32_fp8_sdwa v[114:115], v68 src0_sel:WORD_1
	v_cvt_pk_f32_fp8_e32 v[116:117], v69
	v_cvt_pk_f32_fp8_sdwa v[118:119], v69 src0_sel:WORD_1
	v_cvt_pk_f32_fp8_e32 v[120:121], v70
	v_cvt_pk_f32_fp8_sdwa v[122:123], v70 src0_sel:WORD_1
	v_cvt_pk_f32_fp8_e32 v[124:125], v71
	v_cvt_pk_f32_fp8_sdwa v[126:127], v71 src0_sel:WORD_1
	global_load_dwordx4 v[68:71], v21, s[40:41]
	v_pk_fma_f32 v[0:1], v[112:113], v[36:37], v[0:1] op_sel:[0,1,0] op_sel_hi:[1,1,1]
	v_pk_fma_f32 v[2:3], v[114:115], v[36:37], v[2:3] op_sel:[0,1,0] op_sel_hi:[1,1,1]
	v_pk_fma_f32 v[4:5], v[116:117], v[36:37], v[4:5] op_sel:[0,1,0] op_sel_hi:[1,1,1]
	v_pk_fma_f32 v[6:7], v[118:119], v[36:37], v[6:7] op_sel:[0,1,0] op_sel_hi:[1,1,1]
	v_pk_fma_f32 v[8:9], v[120:121], v[36:37], v[8:9] op_sel:[0,1,0] op_sel_hi:[1,1,1]
	v_pk_fma_f32 v[10:11], v[122:123], v[36:37], v[10:11] op_sel:[0,1,0] op_sel_hi:[1,1,1]
	v_pk_fma_f32 v[12:13], v[124:125], v[36:37], v[12:13] op_sel:[0,1,0] op_sel_hi:[1,1,1]
	v_pk_fma_f32 v[14:15], v[126:127], v[36:37], v[14:15] op_sel:[0,1,0] op_sel_hi:[1,1,1]
	s_waitcnt vmcnt(21)
	v_cvt_pk_f32_fp8_e32 v[112:113], v72
	v_cvt_pk_f32_fp8_sdwa v[114:115], v72 src0_sel:WORD_1
	v_cvt_pk_f32_fp8_e32 v[116:117], v73
	v_cvt_pk_f32_fp8_sdwa v[118:119], v73 src0_sel:WORD_1
	v_cvt_pk_f32_fp8_e32 v[120:121], v74
	v_cvt_pk_f32_fp8_sdwa v[122:123], v74 src0_sel:WORD_1
	v_cvt_pk_f32_fp8_e32 v[124:125], v75
	v_cvt_pk_f32_fp8_sdwa v[126:127], v75 src0_sel:WORD_1
	global_load_dwordx4 v[72:75], v22, s[40:41]
	v_pk_fma_f32 v[0:1], v[112:113], v[38:39], v[0:1] op_sel_hi:[1,0,1]
	v_pk_fma_f32 v[2:3], v[114:115], v[38:39], v[2:3] op_sel_hi:[1,0,1]
	v_pk_fma_f32 v[4:5], v[116:117], v[38:39], v[4:5] op_sel_hi:[1,0,1]
	v_pk_fma_f32 v[6:7], v[118:119], v[38:39], v[6:7] op_sel_hi:[1,0,1]
	v_pk_fma_f32 v[8:9], v[120:121], v[38:39], v[8:9] op_sel_hi:[1,0,1]
	v_pk_fma_f32 v[10:11], v[122:123], v[38:39], v[10:11] op_sel_hi:[1,0,1]
	v_pk_fma_f32 v[12:13], v[124:125], v[38:39], v[12:13] op_sel_hi:[1,0,1]
	v_pk_fma_f32 v[14:15], v[126:127], v[38:39], v[14:15] op_sel_hi:[1,0,1]
	s_waitcnt vmcnt(21)
	v_cvt_pk_f32_fp8_e32 v[112:113], v76
	v_cvt_pk_f32_fp8_sdwa v[114:115], v76 src0_sel:WORD_1
	v_cvt_pk_f32_fp8_e32 v[116:117], v77
	v_cvt_pk_f32_fp8_sdwa v[118:119], v77 src0_sel:WORD_1
	v_cvt_pk_f32_fp8_e32 v[120:121], v78
	v_cvt_pk_f32_fp8_sdwa v[122:123], v78 src0_sel:WORD_1
	v_cvt_pk_f32_fp8_e32 v[124:125], v79
	v_cvt_pk_f32_fp8_sdwa v[126:127], v79 src0_sel:WORD_1
	global_load_dwordx4 v[76:79], v23, s[40:41]
	v_pk_fma_f32 v[0:1], v[112:113], v[38:39], v[0:1] op_sel:[0,1,0] op_sel_hi:[1,1,1]
	v_pk_fma_f32 v[2:3], v[114:115], v[38:39], v[2:3] op_sel:[0,1,0] op_sel_hi:[1,1,1]
	v_pk_fma_f32 v[4:5], v[116:117], v[38:39], v[4:5] op_sel:[0,1,0] op_sel_hi:[1,1,1]
	v_pk_fma_f32 v[6:7], v[118:119], v[38:39], v[6:7] op_sel:[0,1,0] op_sel_hi:[1,1,1]
	v_pk_fma_f32 v[8:9], v[120:121], v[38:39], v[8:9] op_sel:[0,1,0] op_sel_hi:[1,1,1]
	v_pk_fma_f32 v[10:11], v[122:123], v[38:39], v[10:11] op_sel:[0,1,0] op_sel_hi:[1,1,1]
	v_pk_fma_f32 v[12:13], v[124:125], v[38:39], v[12:13] op_sel:[0,1,0] op_sel_hi:[1,1,1]
	v_pk_fma_f32 v[14:15], v[126:127], v[38:39], v[14:15] op_sel:[0,1,0] op_sel_hi:[1,1,1]
	s_waitcnt vmcnt(21)
	v_cvt_pk_f32_fp8_e32 v[112:113], v80
	v_cvt_pk_f32_fp8_sdwa v[114:115], v80 src0_sel:WORD_1
	v_cvt_pk_f32_fp8_e32 v[116:117], v81
	v_cvt_pk_f32_fp8_sdwa v[118:119], v81 src0_sel:WORD_1
	v_cvt_pk_f32_fp8_e32 v[120:121], v82
	v_cvt_pk_f32_fp8_sdwa v[122:123], v82 src0_sel:WORD_1
	v_cvt_pk_f32_fp8_e32 v[124:125], v83
	v_cvt_pk_f32_fp8_sdwa v[126:127], v83 src0_sel:WORD_1
	global_load_dwordx4 v[80:83], v24, s[40:41]
	v_pk_fma_f32 v[0:1], v[112:113], v[40:41], v[0:1] op_sel_hi:[1,0,1]
	v_pk_fma_f32 v[2:3], v[114:115], v[40:41], v[2:3] op_sel_hi:[1,0,1]
	v_pk_fma_f32 v[4:5], v[116:117], v[40:41], v[4:5] op_sel_hi:[1,0,1]
	v_pk_fma_f32 v[6:7], v[118:119], v[40:41], v[6:7] op_sel_hi:[1,0,1]
	v_pk_fma_f32 v[8:9], v[120:121], v[40:41], v[8:9] op_sel_hi:[1,0,1]
	v_pk_fma_f32 v[10:11], v[122:123], v[40:41], v[10:11] op_sel_hi:[1,0,1]
	v_pk_fma_f32 v[12:13], v[124:125], v[40:41], v[12:13] op_sel_hi:[1,0,1]
	v_pk_fma_f32 v[14:15], v[126:127], v[40:41], v[14:15] op_sel_hi:[1,0,1]
	s_waitcnt vmcnt(21)
	v_cvt_pk_f32_fp8_e32 v[112:113], v84
	v_cvt_pk_f32_fp8_sdwa v[114:115], v84 src0_sel:WORD_1
	v_cvt_pk_f32_fp8_e32 v[116:117], v85
	v_cvt_pk_f32_fp8_sdwa v[118:119], v85 src0_sel:WORD_1
	v_cvt_pk_f32_fp8_e32 v[120:121], v86
	v_cvt_pk_f32_fp8_sdwa v[122:123], v86 src0_sel:WORD_1
	v_cvt_pk_f32_fp8_e32 v[124:125], v87
	v_cvt_pk_f32_fp8_sdwa v[126:127], v87 src0_sel:WORD_1
	global_load_dwordx4 v[84:87], v25, s[40:41]
	v_pk_fma_f32 v[0:1], v[112:113], v[40:41], v[0:1] op_sel:[0,1,0] op_sel_hi:[1,1,1]
	v_pk_fma_f32 v[2:3], v[114:115], v[40:41], v[2:3] op_sel:[0,1,0] op_sel_hi:[1,1,1]
	v_pk_fma_f32 v[4:5], v[116:117], v[40:41], v[4:5] op_sel:[0,1,0] op_sel_hi:[1,1,1]
	v_pk_fma_f32 v[6:7], v[118:119], v[40:41], v[6:7] op_sel:[0,1,0] op_sel_hi:[1,1,1]
	v_pk_fma_f32 v[8:9], v[120:121], v[40:41], v[8:9] op_sel:[0,1,0] op_sel_hi:[1,1,1]
	v_pk_fma_f32 v[10:11], v[122:123], v[40:41], v[10:11] op_sel:[0,1,0] op_sel_hi:[1,1,1]
	v_pk_fma_f32 v[12:13], v[124:125], v[40:41], v[12:13] op_sel:[0,1,0] op_sel_hi:[1,1,1]
	v_pk_fma_f32 v[14:15], v[126:127], v[40:41], v[14:15] op_sel:[0,1,0] op_sel_hi:[1,1,1]
	s_waitcnt vmcnt(21)
	v_cvt_pk_f32_fp8_e32 v[112:113], v88
	v_cvt_pk_f32_fp8_sdwa v[114:115], v88 src0_sel:WORD_1
	v_cvt_pk_f32_fp8_e32 v[116:117], v89
	v_cvt_pk_f32_fp8_sdwa v[118:119], v89 src0_sel:WORD_1
	v_cvt_pk_f32_fp8_e32 v[120:121], v90
	v_cvt_pk_f32_fp8_sdwa v[122:123], v90 src0_sel:WORD_1
	v_cvt_pk_f32_fp8_e32 v[124:125], v91
	v_cvt_pk_f32_fp8_sdwa v[126:127], v91 src0_sel:WORD_1
	global_load_dwordx4 v[88:91], v26, s[40:41]
	v_pk_fma_f32 v[0:1], v[112:113], v[42:43], v[0:1] op_sel_hi:[1,0,1]
	v_pk_fma_f32 v[2:3], v[114:115], v[42:43], v[2:3] op_sel_hi:[1,0,1]
	v_pk_fma_f32 v[4:5], v[116:117], v[42:43], v[4:5] op_sel_hi:[1,0,1]
	v_pk_fma_f32 v[6:7], v[118:119], v[42:43], v[6:7] op_sel_hi:[1,0,1]
	v_pk_fma_f32 v[8:9], v[120:121], v[42:43], v[8:9] op_sel_hi:[1,0,1]
	v_pk_fma_f32 v[10:11], v[122:123], v[42:43], v[10:11] op_sel_hi:[1,0,1]
	v_pk_fma_f32 v[12:13], v[124:125], v[42:43], v[12:13] op_sel_hi:[1,0,1]
	v_pk_fma_f32 v[14:15], v[126:127], v[42:43], v[14:15] op_sel_hi:[1,0,1]
	s_waitcnt vmcnt(21)
	v_cvt_pk_f32_fp8_e32 v[112:113], v92
	v_cvt_pk_f32_fp8_sdwa v[114:115], v92 src0_sel:WORD_1
	v_cvt_pk_f32_fp8_e32 v[116:117], v93
	v_cvt_pk_f32_fp8_sdwa v[118:119], v93 src0_sel:WORD_1
	v_cvt_pk_f32_fp8_e32 v[120:121], v94
	v_cvt_pk_f32_fp8_sdwa v[122:123], v94 src0_sel:WORD_1
	v_cvt_pk_f32_fp8_e32 v[124:125], v95
	v_cvt_pk_f32_fp8_sdwa v[126:127], v95 src0_sel:WORD_1
	global_load_dwordx4 v[92:95], v27, s[40:41]
	v_pk_fma_f32 v[0:1], v[112:113], v[42:43], v[0:1] op_sel:[0,1,0] op_sel_hi:[1,1,1]
	v_pk_fma_f32 v[2:3], v[114:115], v[42:43], v[2:3] op_sel:[0,1,0] op_sel_hi:[1,1,1]
	v_pk_fma_f32 v[4:5], v[116:117], v[42:43], v[4:5] op_sel:[0,1,0] op_sel_hi:[1,1,1]
	v_pk_fma_f32 v[6:7], v[118:119], v[42:43], v[6:7] op_sel:[0,1,0] op_sel_hi:[1,1,1]
	v_pk_fma_f32 v[8:9], v[120:121], v[42:43], v[8:9] op_sel:[0,1,0] op_sel_hi:[1,1,1]
	v_pk_fma_f32 v[10:11], v[122:123], v[42:43], v[10:11] op_sel:[0,1,0] op_sel_hi:[1,1,1]
	v_pk_fma_f32 v[12:13], v[124:125], v[42:43], v[12:13] op_sel:[0,1,0] op_sel_hi:[1,1,1]
	v_pk_fma_f32 v[14:15], v[126:127], v[42:43], v[14:15] op_sel:[0,1,0] op_sel_hi:[1,1,1]
	s_waitcnt vmcnt(21)
	v_cvt_pk_f32_fp8_e32 v[112:113], v96
	v_cvt_pk_f32_fp8_sdwa v[114:115], v96 src0_sel:WORD_1
	v_cvt_pk_f32_fp8_e32 v[116:117], v97
	v_cvt_pk_f32_fp8_sdwa v[118:119], v97 src0_sel:WORD_1
	v_cvt_pk_f32_fp8_e32 v[120:121], v98
	v_cvt_pk_f32_fp8_sdwa v[122:123], v98 src0_sel:WORD_1
	v_cvt_pk_f32_fp8_e32 v[124:125], v99
	v_cvt_pk_f32_fp8_sdwa v[126:127], v99 src0_sel:WORD_1
	global_load_dwordx4 v[96:99], v28, s[40:41]
	v_pk_fma_f32 v[0:1], v[112:113], v[44:45], v[0:1] op_sel_hi:[1,0,1]
	v_pk_fma_f32 v[2:3], v[114:115], v[44:45], v[2:3] op_sel_hi:[1,0,1]
	v_pk_fma_f32 v[4:5], v[116:117], v[44:45], v[4:5] op_sel_hi:[1,0,1]
	v_pk_fma_f32 v[6:7], v[118:119], v[44:45], v[6:7] op_sel_hi:[1,0,1]
	v_pk_fma_f32 v[8:9], v[120:121], v[44:45], v[8:9] op_sel_hi:[1,0,1]
	v_pk_fma_f32 v[10:11], v[122:123], v[44:45], v[10:11] op_sel_hi:[1,0,1]
	v_pk_fma_f32 v[12:13], v[124:125], v[44:45], v[12:13] op_sel_hi:[1,0,1]
	v_pk_fma_f32 v[14:15], v[126:127], v[44:45], v[14:15] op_sel_hi:[1,0,1]
	s_waitcnt vmcnt(21)
	v_cvt_pk_f32_fp8_e32 v[112:113], v100
	v_cvt_pk_f32_fp8_sdwa v[114:115], v100 src0_sel:WORD_1
	v_cvt_pk_f32_fp8_e32 v[116:117], v101
	v_cvt_pk_f32_fp8_sdwa v[118:119], v101 src0_sel:WORD_1
	v_cvt_pk_f32_fp8_e32 v[120:121], v102
	v_cvt_pk_f32_fp8_sdwa v[122:123], v102 src0_sel:WORD_1
	v_cvt_pk_f32_fp8_e32 v[124:125], v103
	v_cvt_pk_f32_fp8_sdwa v[126:127], v103 src0_sel:WORD_1
	global_load_dwordx4 v[100:103], v29, s[40:41]
	v_pk_fma_f32 v[0:1], v[112:113], v[44:45], v[0:1] op_sel:[0,1,0] op_sel_hi:[1,1,1]
	v_pk_fma_f32 v[2:3], v[114:115], v[44:45], v[2:3] op_sel:[0,1,0] op_sel_hi:[1,1,1]
	v_pk_fma_f32 v[4:5], v[116:117], v[44:45], v[4:5] op_sel:[0,1,0] op_sel_hi:[1,1,1]
	v_pk_fma_f32 v[6:7], v[118:119], v[44:45], v[6:7] op_sel:[0,1,0] op_sel_hi:[1,1,1]
	v_pk_fma_f32 v[8:9], v[120:121], v[44:45], v[8:9] op_sel:[0,1,0] op_sel_hi:[1,1,1]
	v_pk_fma_f32 v[10:11], v[122:123], v[44:45], v[10:11] op_sel:[0,1,0] op_sel_hi:[1,1,1]
	v_pk_fma_f32 v[12:13], v[124:125], v[44:45], v[12:13] op_sel:[0,1,0] op_sel_hi:[1,1,1]
	v_pk_fma_f32 v[14:15], v[126:127], v[44:45], v[14:15] op_sel:[0,1,0] op_sel_hi:[1,1,1]
	s_waitcnt vmcnt(21)
	v_cvt_pk_f32_fp8_e32 v[112:113], v104
	v_cvt_pk_f32_fp8_sdwa v[114:115], v104 src0_sel:WORD_1
	v_cvt_pk_f32_fp8_e32 v[116:117], v105
	v_cvt_pk_f32_fp8_sdwa v[118:119], v105 src0_sel:WORD_1
	v_cvt_pk_f32_fp8_e32 v[120:121], v106
	v_cvt_pk_f32_fp8_sdwa v[122:123], v106 src0_sel:WORD_1
	v_cvt_pk_f32_fp8_e32 v[124:125], v107
	v_cvt_pk_f32_fp8_sdwa v[126:127], v107 src0_sel:WORD_1
	global_load_dwordx4 v[104:107], v30, s[40:41]
	v_pk_fma_f32 v[0:1], v[112:113], v[46:47], v[0:1] op_sel_hi:[1,0,1]
	v_pk_fma_f32 v[2:3], v[114:115], v[46:47], v[2:3] op_sel_hi:[1,0,1]
	v_pk_fma_f32 v[4:5], v[116:117], v[46:47], v[4:5] op_sel_hi:[1,0,1]
	v_pk_fma_f32 v[6:7], v[118:119], v[46:47], v[6:7] op_sel_hi:[1,0,1]
	v_pk_fma_f32 v[8:9], v[120:121], v[46:47], v[8:9] op_sel_hi:[1,0,1]
	v_pk_fma_f32 v[10:11], v[122:123], v[46:47], v[10:11] op_sel_hi:[1,0,1]
	v_pk_fma_f32 v[12:13], v[124:125], v[46:47], v[12:13] op_sel_hi:[1,0,1]
	v_pk_fma_f32 v[14:15], v[126:127], v[46:47], v[14:15] op_sel_hi:[1,0,1]
	s_waitcnt vmcnt(21)
	v_cvt_pk_f32_fp8_e32 v[112:113], v108
	v_cvt_pk_f32_fp8_sdwa v[114:115], v108 src0_sel:WORD_1
	v_cvt_pk_f32_fp8_e32 v[116:117], v109
	v_cvt_pk_f32_fp8_sdwa v[118:119], v109 src0_sel:WORD_1
	v_cvt_pk_f32_fp8_e32 v[120:121], v110
	v_cvt_pk_f32_fp8_sdwa v[122:123], v110 src0_sel:WORD_1
	v_cvt_pk_f32_fp8_e32 v[124:125], v111
	v_cvt_pk_f32_fp8_sdwa v[126:127], v111 src0_sel:WORD_1
	global_load_dwordx4 v[108:111], v31, s[40:41]
	v_pk_fma_f32 v[0:1], v[112:113], v[46:47], v[0:1] op_sel:[0,1,0] op_sel_hi:[1,1,1]
	v_pk_fma_f32 v[2:3], v[114:115], v[46:47], v[2:3] op_sel:[0,1,0] op_sel_hi:[1,1,1]
	v_pk_fma_f32 v[4:5], v[116:117], v[46:47], v[4:5] op_sel:[0,1,0] op_sel_hi:[1,1,1]
	v_pk_fma_f32 v[6:7], v[118:119], v[46:47], v[6:7] op_sel:[0,1,0] op_sel_hi:[1,1,1]
	v_pk_fma_f32 v[8:9], v[120:121], v[46:47], v[8:9] op_sel:[0,1,0] op_sel_hi:[1,1,1]
	v_pk_fma_f32 v[10:11], v[122:123], v[46:47], v[10:11] op_sel:[0,1,0] op_sel_hi:[1,1,1]
	v_pk_fma_f32 v[12:13], v[124:125], v[46:47], v[12:13] op_sel:[0,1,0] op_sel_hi:[1,1,1]
	v_pk_fma_f32 v[14:15], v[126:127], v[46:47], v[14:15] op_sel:[0,1,0] op_sel_hi:[1,1,1]
	s_nop 1
	v_permlane32_swap_b32_e32 v0, v8
	v_permlane32_swap_b32_e32 v1, v9
	v_permlane32_swap_b32_e32 v2, v10
	v_permlane32_swap_b32_e32 v3, v11
	v_permlane32_swap_b32_e32 v4, v12
	v_permlane32_swap_b32_e32 v5, v13
	v_permlane32_swap_b32_e32 v6, v14
	v_permlane32_swap_b32_e32 v7, v15
	v_add_f32_e32 v0, v0, v8
	v_add_f32_e32 v1, v1, v9
	v_add_f32_e32 v2, v2, v10
	v_add_f32_e32 v3, v3, v11
	v_add_f32_e32 v4, v4, v12
	v_add_f32_e32 v5, v5, v13
	v_add_f32_e32 v6, v6, v14
	v_add_f32_e32 v7, v7, v15
	s_nop 1
	v_permlane16_swap_b32_e32 v0, v4
	v_permlane16_swap_b32_e32 v1, v5
	v_permlane16_swap_b32_e32 v2, v6
	v_permlane16_swap_b32_e32 v3, v7
	v_add_f32_e32 v0, v0, v4
	v_add_f32_e32 v1, v1, v5
	v_add_f32_e32 v2, v2, v6
	v_add_f32_e32 v3, v3, v7
	s_nop 1
	v_add_f32_dpp v142, v0, v0 row_ror:8 row_mask:0xf bank_mask:0x3
	v_add_f32_dpp v142, v2, v2 row_ror:8 row_mask:0xf bank_mask:0xc
	v_add_f32_dpp v143, v1, v1 row_ror:8 row_mask:0xf bank_mask:0x3
	v_add_f32_dpp v143, v3, v3 row_ror:8 row_mask:0xf bank_mask:0xc
	v_mov_b32_e32 v0, v142
	v_mov_b32_e32 v1, v143
	s_waitcnt vmcnt(16)
	v_mul_f32_e32 v192, v0, v192
	v_mul_f32_e32 v193, v1, v193
	v_fma_f32 v190, v190, s16, v192
	v_fma_f32 v191, v191, s16, v193
	s_lshl_b32 s98, s54, 12
	s_add_u32 s52, s92, s98
	s_addc_u32 s53, s93, 0
	global_store_dwordx2 v188, v[190:191], s[52:53]
	s_waitcnt vmcnt(16)
	ds_bpermute_b32 v16, v130, v150
	ds_bpermute_b32 v17, v131, v150
	ds_bpermute_b32 v18, v132, v150
	ds_bpermute_b32 v19, v133, v150
	ds_bpermute_b32 v20, v134, v150
	ds_bpermute_b32 v21, v135, v150
	ds_bpermute_b32 v22, v136, v150
	ds_bpermute_b32 v23, v137, v150
	ds_bpermute_b32 v24, v130, v151
	ds_bpermute_b32 v25, v131, v151
	ds_bpermute_b32 v26, v132, v151
	ds_bpermute_b32 v27, v133, v151
	ds_bpermute_b32 v28, v134, v151
	ds_bpermute_b32 v29, v135, v151
	ds_bpermute_b32 v30, v136, v151
	ds_bpermute_b32 v31, v137, v151
	s_waitcnt lgkmcnt(0)
	v_lshl_add_u32 v16, v16, 10, v138
	v_lshl_add_u32 v17, v17, 10, v138
	v_lshl_add_u32 v18, v18, 10, v138
	v_lshl_add_u32 v19, v19, 10, v138
	v_lshl_add_u32 v20, v20, 10, v138
	v_lshl_add_u32 v21, v21, 10, v138
	v_lshl_add_u32 v22, v22, 10, v138
	v_lshl_add_u32 v23, v23, 10, v138
	v_lshl_add_u32 v24, v24, 10, v138
	v_lshl_add_u32 v25, v25, 10, v138
	v_lshl_add_u32 v26, v26, 10, v138
	v_lshl_add_u32 v27, v27, 10, v138
	v_lshl_add_u32 v28, v28, 10, v138
	v_lshl_add_u32 v29, v29, 10, v138
	v_lshl_add_u32 v30, v30, 10, v138
	v_lshl_add_u32 v31, v31, 10, v138
	ds_bpermute_b32 v32, v130, v194
	ds_bpermute_b32 v33, v131, v194
	ds_bpermute_b32 v34, v132, v194
	ds_bpermute_b32 v35, v133, v194
	ds_bpermute_b32 v36, v134, v194
	ds_bpermute_b32 v37, v135, v194
	ds_bpermute_b32 v38, v136, v194
	ds_bpermute_b32 v39, v137, v194
	ds_bpermute_b32 v40, v130, v195
	ds_bpermute_b32 v41, v131, v195
	ds_bpermute_b32 v42, v132, v195
	ds_bpermute_b32 v43, v133, v195
	ds_bpermute_b32 v44, v134, v195
	ds_bpermute_b32 v45, v135, v195
	ds_bpermute_b32 v46, v136, v195
	ds_bpermute_b32 v47, v137, v195
	s_mov_b32 s54, s99
	s_cmp_lt_u32 s54, 0x4200
	s_cbranch_scc1 .Lgy_Ctok_11
